# diff-attn loop: mask / rescale / no-write blocks moved out of line so the common path takes no branch
# baseline (speedup 1.0000x reference)
; __device__ __forceinline__ void finishSM(f32x16& p0, f32x16& p1, float alpha, float& l_reg, bf16x8& pa0, bf16x8& pa1, bf16x8& pa2, bf16x8& pa3) {
;     for (int r = 0; r < 16; ++r) p1[r] = __builtin_amdgcn_exp2f(p1[r]);
;     float ps = 0; for (int r = 0; r < 16; ++r) ps += p0[r]; for (int r = 0; r < 16; ++r) ps += p1[r];
;     { auto rr = __builtin_amdgcn_permlane32_swap(__float_as_uint(ps), __float_as_uint(ps), false, false);
;       ps = __uint_as_float(rr[0]) + __uint_as_float(rr[1]); }
;     l_reg = l_reg * alpha + ps;
;     ...
;     PK4(p0, 0, pa0); PK4(p0, 8, pa1); PK4(p1, 0, pa2); PK4(p1, 8, pa3);
;     ...
; }
; template <int KB, bool SK>
; __device__ __forceinline__ void qkt(f32x16& p0, f32x16& p1, const char* K_lds, int r32, int hi, const bf16x8* qr, bool act) {
;     if (SK && !act) { const float NEG = -__builtin_inff();
; #pragma unroll
;         for (int r = 0; r < 16; ++r) { p0[r] = NEG; p1[r] = NEG; } return; }
;     p0 = f32x16{}; p1 = f32x16{};
;     const char* kb[4];
; #pragma unroll
;     for (int dd = 0; dd < 4; ++dd) kb[dd] = K_lds + KB * SHM_K + KSWZ(r32, (dd * 16 + hi * 8) * 2);
; #pragma unroll
;     for (int d0 = 0; d0 < 8; ++d0) { const char* a = kb[d0 & 3] + (d0 >> 2) * 128;
;         bf16x8 b0 = *reinterpret_cast<const bf16x8*>(a);
;         bf16x8 b1 = *reinterpret_cast<const bf16x8*>(a + 32 * 256);
;         const bf16x8 qf = qr[d0];
;         p0 = __builtin_amdgcn_mfma_f32_32x32x16_bf16(b0, qf, p0, 0, 0, 0);
;         p1 = __builtin_amdgcn_mfma_f32_32x32x16_bf16(b1, qf, p1, 0, 0, 0); }
; }
.Lattn_prio_skip:
.LBB0_1129:
	ds_read_b128 v[180:183], v211 offset:49152
	ds_read_b128 v[184:187], v211 offset:57344
	ds_read_b128 v[188:191], v212 offset:49152
	ds_read_b128 v[228:231], v212 offset:57344
	ds_read_b128 v[232:235], v213 offset:49152
	ds_read_b128 v[236:239], v213 offset:57344
	ds_read_b128 v[240:243], v214 offset:49152
	ds_read_b128 v[244:247], v214 offset:57344
	v_exp_f32_e32 v126, v126
	v_exp_f32_e32 v127, v127
	v_exp_f32_e32 v124, v124
	v_exp_f32_e32 v125, v125
	v_exp_f32_e32 v120, v120
	v_exp_f32_e32 v121, v121
	s_add_i32 s4, s26, 0xffffff81
	s_sub_i32 s5, s26, 64
	s_waitcnt lgkmcnt(7)
	v_mfma_f32_32x32x16_bf16 v[86:101], v[180:183], v[158:161], 0
	ds_read_b128 v[180:183], v211 offset:49280
	v_exp_f32_e32 v116, v116
	v_exp_f32_e32 v117, v117
	v_exp_f32_e32 v114, v114
	v_exp_f32_e32 v115, v115
	v_exp_f32_e32 v128, v128
	s_waitcnt lgkmcnt(7)
	v_mfma_f32_32x32x16_bf16 v[70:85], v[184:187], v[158:161], 0
	ds_read_b128 v[184:187], v211 offset:57472
	v_exp_f32_e32 v129, v129
	v_exp_f32_e32 v122, v122
	v_exp_f32_e32 v123, v123
	v_exp_f32_e32 v118, v118
	v_exp_f32_e32 v119, v119
	s_waitcnt lgkmcnt(7)
	v_mfma_f32_32x32x16_bf16 v[86:101], v[188:191], v[154:157], v[86:101]
	ds_read_b128 v[188:191], v212 offset:49280
	v_add_f32_e32 v179, 0, v170
	v_add_f32_e32 v179, v171, v179
	v_add_f32_e32 v179, v172, v179
	v_add_f32_e32 v179, v173, v179
	v_add_f32_e32 v179, v174, v179
	s_waitcnt lgkmcnt(7)
	v_mfma_f32_32x32x16_bf16 v[70:85], v[228:231], v[154:157], v[70:85]
	ds_read_b128 v[228:231], v212 offset:57472
	v_add_f32_e32 v179, v176, v179
	v_add_f32_e32 v179, v175, v179
	v_add_f32_e32 v179, v177, v179
	v_add_f32_e32 v179, v162, v179
	v_add_f32_e32 v179, v163, v179
	s_waitcnt lgkmcnt(7)
	v_mfma_f32_32x32x16_bf16 v[86:101], v[232:235], v[150:153], v[86:101]
	ds_read_b128 v[232:235], v213 offset:49280
	v_add_f32_e32 v110, v164, v179
	v_add_f32_e32 v110, v166, v110
	v_add_f32_e32 v110, v165, v110
	v_add_f32_e32 v110, v167, v110
	s_waitcnt lgkmcnt(7)
	v_mfma_f32_32x32x16_bf16 v[70:85], v[236:239], v[150:153], v[70:85]
	ds_read_b128 v[236:239], v213 offset:57472
	v_add_f32_e32 v110, v168, v110
	v_add_f32_e32 v110, v169, v110
	v_add_f32_e32 v110, v126, v110
	v_add_f32_e32 v102, v127, v110
	s_waitcnt lgkmcnt(7)
	v_mfma_f32_32x32x16_bf16 v[86:101], v[240:243], v[134:137], v[86:101]
	ds_read_b128 v[240:243], v214 offset:49280
	v_add_f32_e32 v102, v124, v102
	v_add_f32_e32 v102, v125, v102
	v_add_f32_e32 v102, v120, v102
	v_add_f32_e32 v102, v121, v102
	s_waitcnt lgkmcnt(7)
	v_mfma_f32_32x32x16_bf16 v[70:85], v[244:247], v[134:137], v[70:85]
	ds_read_b128 v[244:247], v214 offset:57472
	v_add_f32_e32 v102, v116, v102
	v_add_f32_e32 v102, v117, v102
	v_add_f32_e32 v102, v114, v102
	v_add_f32_e32 v102, v115, v102
	s_waitcnt lgkmcnt(7)
	v_mfma_f32_32x32x16_bf16 v[86:101], v[180:183], v[138:141], v[86:101]
	v_add_f32_e32 v102, v128, v102
	v_add_f32_e32 v102, v129, v102
	v_add_f32_e32 v102, v122, v102
	v_add_f32_e32 v102, v123, v102
	s_waitcnt lgkmcnt(6)
	v_mfma_f32_32x32x16_bf16 v[70:85], v[184:187], v[138:141], v[70:85]
	v_add_f32_e32 v102, v118, v102
	v_add_f32_e32 v223, v119, v102
	v_mov_b32_e32 v224, v223
	s_nop 1
	v_permlane32_swap_b32_e32 v223, v224
	s_waitcnt lgkmcnt(5)
	v_mfma_f32_32x32x16_bf16 v[86:101], v[188:191], v[142:145], v[86:101]
	v_cvt_pk_bf16_f32 v102, v170, v171
	v_cvt_pk_bf16_f32 v103, v172, v173
	v_cvt_pk_bf16_f32 v104, v174, v176
	v_cvt_pk_bf16_f32 v105, v175, v177
	s_waitcnt lgkmcnt(4)
	v_mfma_f32_32x32x16_bf16 v[70:85], v[228:231], v[142:145], v[70:85]
	v_cvt_pk_bf16_f32 v66, v162, v163
	v_cvt_pk_bf16_f32 v67, v164, v166
	v_cvt_pk_bf16_f32 v68, v165, v167
	v_cvt_pk_bf16_f32 v69, v168, v169
	s_waitcnt lgkmcnt(3)
	v_mfma_f32_32x32x16_bf16 v[86:101], v[232:235], v[146:149], v[86:101]
	v_cvt_pk_bf16_f32 v106, v126, v127
	v_cvt_pk_bf16_f32 v107, v124, v125
	v_cvt_pk_bf16_f32 v108, v120, v121
	v_cvt_pk_bf16_f32 v109, v116, v117
	s_waitcnt lgkmcnt(2)
	v_mfma_f32_32x32x16_bf16 v[70:85], v[236:239], v[146:149], v[70:85]
	v_cvt_pk_bf16_f32 v110, v114, v115
	v_cvt_pk_bf16_f32 v111, v128, v129
	v_cvt_pk_bf16_f32 v112, v122, v123
	v_cvt_pk_bf16_f32 v113, v118, v119
	s_waitcnt lgkmcnt(1)
	v_mfma_f32_32x32x16_bf16 v[86:101], v[240:243], v[130:133], v[86:101]
	s_nop 1
	v_permlane32_swap_b32_e32 v102, v104
	v_permlane32_swap_b32_e32 v103, v105
	v_permlane32_swap_b32_e32 v66, v68
	v_permlane32_swap_b32_e32 v67, v69
	s_waitcnt lgkmcnt(0)
	v_mfma_f32_32x32x16_bf16 v[70:85], v[244:247], v[130:133], v[70:85]
	v_permlane32_swap_b32_e32 v106, v108
	v_permlane32_swap_b32_e32 v107, v109
	v_permlane32_swap_b32_e32 v110, v112
	v_permlane32_swap_b32_e32 v111, v113
	v_add_u32_e32 v114, 0x2000, v255
	global_load_dwordx4 v[162:165], v255, s[42:43]
	global_load_dwordx4 v[166:169], v114, s[42:43]
	global_load_dwordx4 v[170:173], v255, s[22:23]
	global_load_dwordx4 v[174:177], v114, s[22:23]
	s_cmp_le_i32 s5, s13
	s_cselect_b64 s[52:53], -1, 0
	s_cmp_gt_i32 s4, s15
	s_cselect_b64 s[4:5], -1, 0
	s_and_b64 s[4:5], s[52:53], s[4:5]
	s_and_b64 vcc, exec, s[4:5]
	ds_read_b64_tr_b16 v[114:115], v202 offset:0x0
	ds_read_b64_tr_b16 v[116:117], v202 offset:0x800
	ds_read_b64_tr_b16 v[118:119], v202 offset:0x1000
	ds_read_b64_tr_b16 v[120:121], v202 offset:0x1800
	ds_read_b64_tr_b16 v[122:123], v202 offset:0x2000
	ds_read_b64_tr_b16 v[124:125], v202 offset:0x2800
	ds_read_b64_tr_b16 v[126:127], v202 offset:0x3000
	ds_read_b64_tr_b16 v[128:129], v202 offset:0x3800
	ds_read_b64_tr_b16 v[182:183], v202 offset:0x200
	ds_read_b64_tr_b16 v[184:185], v202 offset:0xa00
	ds_read_b64_tr_b16 v[186:187], v202 offset:0x1200
	ds_read_b64_tr_b16 v[188:189], v202 offset:0x1a00
	ds_read_b64_tr_b16 v[190:191], v202 offset:0x2200
	ds_read_b64_tr_b16 v[192:193], v202 offset:0x2a00
	s_cbranch_vccz .Lh1_mask

; template <int VB, bool SK>
; __device__ __forceinline__ void pv_tile(f32x16* o, int vb0, bf16x8 pa0, bf16x8 pa1, bf16x8 pa2, bf16x8 pa3, bool act) {
;     if (SK && !act) return;
;     ...
;     PV_D0(0); PV_D0(1); PV_D0(2); PV_D0(3);
;     ...
; }
.Lh1_back:
	v_fmamk_f32 v228, v86, 0x3e0293ee, v253
	v_fmamk_f32 v229, v87, 0x3e0293ee, v253
	s_waitcnt lgkmcnt(12)
	v_mfma_f32_32x32x16_bf16 v[50:65], v[66:69], v[186:189], v[50:65]
	ds_read_b64_tr_b16 v[182:183], v202 offset:0x600
	ds_read_b64_tr_b16 v[184:185], v202 offset:0xe00
	v_fmamk_f32 v230, v88, 0x3e0293ee, v253
	v_fmamk_f32 v231, v89, 0x3e0293ee, v253
	v_fmamk_f32 v232, v90, 0x3e0293ee, v253
	s_waitcnt lgkmcnt(12)
	v_mfma_f32_32x32x16_bf16 v[50:65], v[106:109], v[190:193], v[50:65]
	ds_read_b64_tr_b16 v[186:187], v202 offset:0x1600
	ds_read_b64_tr_b16 v[188:189], v202 offset:0x1e00
	v_fmamk_f32 v233, v91, 0x3e0293ee, v253
	v_fmamk_f32 v234, v92, 0x3e0293ee, v253
	v_fmamk_f32 v235, v93, 0x3e0293ee, v253
	s_waitcnt lgkmcnt(12)
	v_mfma_f32_32x32x16_bf16 v[50:65], v[110:113], v[244:247], v[50:65]
	ds_read_b64_tr_b16 v[190:191], v202 offset:0x2600
	ds_read_b64_tr_b16 v[192:193], v202 offset:0x2e00
	v_fmamk_f32 v236, v94, 0x3e0293ee, v253
	v_fmamk_f32 v237, v95, 0x3e0293ee, v253
	v_fmamk_f32 v238, v96, 0x3e0293ee, v253
	s_waitcnt lgkmcnt(12)
	v_mfma_f32_32x32x16_bf16 v[18:33], v[102:105], v[114:117], v[18:33]
	ds_read_b64_tr_b16 v[244:245], v202 offset:0x3600
	ds_read_b64_tr_b16 v[246:247], v202 offset:0x3e00
	v_fmamk_f32 v239, v97, 0x3e0293ee, v253
	v_fmamk_f32 v98, v98, 0x3e0293ee, v253
	v_fmamk_f32 v99, v99, 0x3e0293ee, v253
	s_waitcnt lgkmcnt(12)
	v_mfma_f32_32x32x16_bf16 v[18:33], v[66:69], v[118:121], v[18:33]
	v_fmamk_f32 v100, v100, 0x3e0293ee, v253
	v_fmamk_f32 v101, v101, 0x3e0293ee, v253
	v_fmamk_f32 v86, v70, 0x3e0293ee, v253
	s_waitcnt lgkmcnt(10)
	v_mfma_f32_32x32x16_bf16 v[18:33], v[106:109], v[122:125], v[18:33]
	v_fmamk_f32 v95, v71, 0x3e0293ee, v253
	v_fmamk_f32 v96, v72, 0x3e0293ee, v253
	v_fmamk_f32 v97, v73, 0x3e0293ee, v253
	s_waitcnt lgkmcnt(8)
	v_mfma_f32_32x32x16_bf16 v[18:33], v[110:113], v[126:129], v[18:33]
	v_fmamk_f32 v179, v74, 0x3e0293ee, v253
	v_fmamk_f32 v87, v75, 0x3e0293ee, v253
	v_fmamk_f32 v88, v76, 0x3e0293ee, v253
	s_waitcnt lgkmcnt(0)
	s_barrier
	s_waitcnt vmcnt(0)
	v_mfma_f32_32x32x16_bf16 v[2:17], v[102:105], v[182:185], v[2:17]
	ds_write_b128 v209, v[162:165]
	v_fmamk_f32 v89, v77, 0x3e0293ee, v253
	v_fmamk_f32 v90, v78, 0x3e0293ee, v253
	v_fmamk_f32 v91, v79, 0x3e0293ee, v253
	v_mfma_f32_32x32x16_bf16 v[2:17], v[66:69], v[186:189], v[2:17]
	ds_write_b128 v210, v[166:169]
	v_fmamk_f32 v92, v80, 0x3e0293ee, v253
	v_fmamk_f32 v93, v81, 0x3e0293ee, v253
	v_fmamk_f32 v94, v82, 0x3e0293ee, v253
	v_mfma_f32_32x32x16_bf16 v[2:17], v[106:109], v[190:193], v[2:17]
	ds_write_b128 v217, v[170:173] offset:32768
	v_fmamk_f32 v180, v83, 0x3e0293ee, v253
	v_fmamk_f32 v181, v84, 0x3e0293ee, v253
	v_fmamk_f32 v178, v85, 0x3e0293ee, v253
	v_mfma_f32_32x32x16_bf16 v[2:17], v[110:113], v[244:247], v[2:17]
	ds_write_b128 v217, v[174:177] offset:40960
	s_and_b64 vcc, exec, s[4:5]
	s_cbranch_vccz .Lh1_resc

; template <int VB, bool SK>
; __device__ __forceinline__ void pv_tile(f32x16* o, int vb0, bf16x8 pa0, bf16x8 pa1, bf16x8 pa2, bf16x8 pa3, bool act) {
;     if (SK && !act) return;
;     ...
;     PV_D0(0); PV_D0(1); PV_D0(2); PV_D0(3);
.LBB0_1137:
	s_sub_i32 s27, s26, 63
	s_cmp_le_i32 s26, s13
	s_cselect_b64 s[4:5], -1, 0
	s_cmp_gt_i32 s27, s15
	s_cselect_b64 s[52:53], -1, 0
	s_and_b64 s[4:5], s[4:5], s[52:53]
	s_and_b64 vcc, exec, s[4:5]
	ds_read_b64_tr_b16 v[230:231], v202 offset:0x4000
	ds_read_b64_tr_b16 v[232:233], v202 offset:0x4800
	ds_read_b64_tr_b16 v[234:235], v202 offset:0x5000
	ds_read_b64_tr_b16 v[236:237], v202 offset:0x5800
	ds_read_b64_tr_b16 v[238:239], v202 offset:0x6000
	ds_read_b64_tr_b16 v[240:241], v202 offset:0x6800
	ds_read_b64_tr_b16 v[242:243], v202 offset:0x7000
	ds_read_b64_tr_b16 v[244:245], v202 offset:0x7800
	ds_read_b64_tr_b16 v[86:87], v202 offset:0x4200
	ds_read_b64_tr_b16 v[88:89], v202 offset:0x4a00
	ds_read_b64_tr_b16 v[90:91], v202 offset:0x5200
	ds_read_b64_tr_b16 v[92:93], v202 offset:0x5a00
	ds_read_b64_tr_b16 v[94:95], v202 offset:0x6200
	ds_read_b64_tr_b16 v[96:97], v202 offset:0x6a00
	s_cbranch_vccz .Lh2_mask

; template <class TIn, class TOut>
; __device__ __forceinline__ void causal_swa_block(const BlockRef<TIn, TOut>& cur, const BlockRef<TIn, TOut>& nxt, int skv, int W, char* lds, Seam<TIn>& S) {
;     ...
;     for (int t = 1; t + 1 < NT; t += 2) {
;         HALF_STEP(pB0, pB1, mnB, alB, pA0, pA1, alA, t, 1, 0, 0);
;         HALF_STEP(pA0, pA1, mnA, alA, pB0, pB1, alB, t + 1, 0, 1, 1);
.Lh2_pvt_join:
.Lh2_nowrite:
	v_add_u32_e32 v194, 0x4000, v194
	v_add_u32_e32 v222, 0xffffff80, v222
	v_add_u32_e32 v255, 0x8000, v255
	s_addk_i32 s26, 0x80
	s_add_i32 s25, s25, 2
	s_and_b64 vcc, exec, s[4:5]
	s_cbranch_vccz .Lh2_resc

; __device__ __forceinline__ void mask_tile(f32x16& p0, f32x16& p1, int dq, unsigned W) {
;     const float NEG = -__builtin_inff();
; #pragma unroll
;     for (int r = 0; r < 16; ++r) {
;         const int c = (r & 3) + 8 * (r >> 2);
;         if ((unsigned)(dq - c) >= W) p0[r] = NEG;
;         if ((unsigned)(dq - c - 32) >= W) p1[r] = NEG;
;     }
; }
.Lh1_mask:
	v_add_u32_e32 v226, s80, v222
	v_subrev_u32_e32 v240, 64, v226
	v_cmp_gt_u32_e32 vcc, s85, v240
	v_add_u32_e32 v240, 0xffffffa0, v226
	s_nop 0
	v_cndmask_b32_e32 v86, v215, v86, vcc
	v_cmp_gt_u32_e32 vcc, s85, v240
	v_add_u32_e32 v240, 0xffffffbf, v226
	s_nop 0
	v_cndmask_b32_e32 v70, v215, v70, vcc
	v_cmp_gt_u32_e32 vcc, s85, v240
	v_add_u32_e32 v240, 0xffffff9f, v226
	s_nop 0
	v_cndmask_b32_e32 v87, v215, v87, vcc
	v_cmp_gt_u32_e32 vcc, s85, v240
	v_add_u32_e32 v240, 0xffffffbe, v226
	s_nop 0
	v_cndmask_b32_e32 v71, v215, v71, vcc
	v_cmp_gt_u32_e32 vcc, s85, v240
	v_add_u32_e32 v240, 0xffffff9e, v226
	s_nop 0
	v_cndmask_b32_e32 v88, v215, v88, vcc
	v_cmp_gt_u32_e32 vcc, s85, v240
	v_add_u32_e32 v240, 0xffffffbd, v226
	s_nop 0
	v_cndmask_b32_e32 v72, v215, v72, vcc
	v_cmp_gt_u32_e32 vcc, s85, v240
	v_add_u32_e32 v240, 0xffffff9d, v226
	s_nop 0
	v_cndmask_b32_e32 v89, v215, v89, vcc
	v_cmp_gt_u32_e32 vcc, s85, v240
	v_add_u32_e32 v240, 0xffffffb8, v226
	s_nop 0
	v_cndmask_b32_e32 v73, v215, v73, vcc
	v_cmp_gt_u32_e32 vcc, s85, v240
	v_add_u32_e32 v240, 0xffffff98, v226
	s_nop 0
	v_cndmask_b32_e32 v90, v215, v90, vcc
	v_cmp_gt_u32_e32 vcc, s85, v240
	v_add_u32_e32 v240, 0xffffffb7, v226
	s_nop 0
	v_cndmask_b32_e32 v74, v215, v74, vcc
	v_cmp_gt_u32_e32 vcc, s85, v240
	v_add_u32_e32 v240, 0xffffff97, v226
	s_nop 0
	v_cndmask_b32_e32 v91, v215, v91, vcc
	v_cmp_gt_u32_e32 vcc, s85, v240
	v_add_u32_e32 v240, 0xffffffb6, v226
	s_nop 0
	v_cndmask_b32_e32 v75, v215, v75, vcc
	v_cmp_gt_u32_e32 vcc, s85, v240
	v_add_u32_e32 v240, 0xffffff96, v226
	s_nop 0
	v_cndmask_b32_e32 v92, v215, v92, vcc
	v_cmp_gt_u32_e32 vcc, s85, v240
	v_add_u32_e32 v240, 0xffffffb5, v226
	s_nop 0
	v_cndmask_b32_e32 v76, v215, v76, vcc
	v_cmp_gt_u32_e32 vcc, s85, v240
	v_add_u32_e32 v240, 0xffffff95, v226
	s_nop 0
	v_cndmask_b32_e32 v93, v215, v93, vcc
	v_cmp_gt_u32_e32 vcc, s85, v240
	v_add_u32_e32 v240, 0xffffffb0, v226
	s_nop 0
	v_cndmask_b32_e32 v77, v215, v77, vcc
	v_cmp_gt_u32_e32 vcc, s85, v240
	v_add_u32_e32 v240, 0xffffff90, v226
	s_nop 0
	v_cndmask_b32_e32 v94, v215, v94, vcc
	v_cmp_gt_u32_e32 vcc, s85, v240
	v_add_u32_e32 v240, 0xffffffaf, v226
	s_nop 0
	v_cndmask_b32_e32 v78, v215, v78, vcc
	v_cmp_gt_u32_e32 vcc, s85, v240
	v_add_u32_e32 v240, 0xffffff8f, v226
	s_nop 0
	v_cndmask_b32_e32 v95, v215, v95, vcc
	v_cmp_gt_u32_e32 vcc, s85, v240
	v_add_u32_e32 v240, 0xffffffae, v226
	s_nop 0
	v_cndmask_b32_e32 v79, v215, v79, vcc
	v_cmp_gt_u32_e32 vcc, s85, v240
	v_add_u32_e32 v240, 0xffffff8e, v226
	s_nop 0
	v_cndmask_b32_e32 v96, v215, v96, vcc
	v_cmp_gt_u32_e32 vcc, s85, v240
	v_add_u32_e32 v240, 0xffffffad, v226
	s_nop 0
	v_cndmask_b32_e32 v80, v215, v80, vcc
	v_cmp_gt_u32_e32 vcc, s85, v240
	v_add_u32_e32 v240, 0xffffff8d, v226
	s_nop 0
	v_cndmask_b32_e32 v97, v215, v97, vcc
	v_cmp_gt_u32_e32 vcc, s85, v240
	v_add_u32_e32 v240, 0xffffffa8, v226
	s_nop 0
	v_cndmask_b32_e32 v81, v215, v81, vcc
	v_cmp_gt_u32_e32 vcc, s85, v240
	v_add_u32_e32 v240, 0xffffff88, v226
	s_nop 0
	v_cndmask_b32_e32 v98, v215, v98, vcc
	v_cmp_gt_u32_e32 vcc, s85, v240
	v_add_u32_e32 v240, 0xffffffa7, v226
	s_nop 0
	v_cndmask_b32_e32 v82, v215, v82, vcc
	v_cmp_gt_u32_e32 vcc, s85, v240
	v_add_u32_e32 v240, 0xffffff87, v226
	s_nop 0
	v_cndmask_b32_e32 v99, v215, v99, vcc
	v_cmp_gt_u32_e32 vcc, s85, v240
	v_add_u32_e32 v240, 0xffffffa6, v226
	s_nop 0
	v_cndmask_b32_e32 v83, v215, v83, vcc
	v_cmp_gt_u32_e32 vcc, s85, v240
	v_add_u32_e32 v240, 0xffffff86, v226
	s_nop 0
	v_cndmask_b32_e32 v100, v215, v100, vcc
	v_cmp_gt_u32_e32 vcc, s85, v240
	v_add_u32_e32 v240, 0xffffffa5, v226
	s_nop 0
	v_cndmask_b32_e32 v84, v215, v84, vcc
	v_cmp_gt_u32_e32 vcc, s85, v240
	v_add_u32_e32 v240, 0xffffff85, v226
	s_nop 0
	v_cndmask_b32_e32 v101, v215, v101, vcc
	v_cmp_gt_u32_e32 vcc, s85, v240
	s_nop 1
	v_cndmask_b32_e32 v85, v215, v85, vcc
	s_branch .Lh1_nomask
.Lh1_resc:
	s_and_saveexec_b64 s[52:53], s[0:1]
	ds_write_b32 v219, v225 offset:128
	s_or_b64 exec, exec, s[52:53]
	s_waitcnt lgkmcnt(0)
	ds_read_b128 v[102:105], v218 offset:224
	ds_read_b128 v[106:109], v218 offset:192
	ds_read_b128 v[110:113], v218 offset:160
	ds_read_b128 v[114:117], v218 offset:128
	s_waitcnt lgkmcnt(3)
	v_pk_mul_f32 v[48:49], v[48:49], v[104:105]
	s_waitcnt lgkmcnt(2)
	v_pk_mul_f32 v[44:45], v[44:45], v[108:109]
	s_waitcnt lgkmcnt(1)
	v_pk_mul_f32 v[40:41], v[40:41], v[112:113]
	s_waitcnt lgkmcnt(0)
	v_pk_mul_f32 v[36:37], v[36:37], v[116:117]
	v_pk_mul_f32 v[46:47], v[46:47], v[102:103]
	v_pk_mul_f32 v[42:43], v[42:43], v[106:107]
	v_pk_mul_f32 v[38:39], v[38:39], v[110:111]
	v_pk_mul_f32 v[34:35], v[34:35], v[114:115]
	v_pk_mul_f32 v[64:65], v[64:65], v[104:105]
	v_pk_mul_f32 v[60:61], v[60:61], v[108:109]
	v_pk_mul_f32 v[56:57], v[56:57], v[112:113]
	v_pk_mul_f32 v[52:53], v[52:53], v[116:117]
	v_pk_mul_f32 v[62:63], v[62:63], v[102:103]
	v_pk_mul_f32 v[58:59], v[58:59], v[106:107]
	v_pk_mul_f32 v[54:55], v[54:55], v[110:111]
	v_pk_mul_f32 v[50:51], v[50:51], v[114:115]
	v_pk_mul_f32 v[32:33], v[32:33], v[104:105]
	v_pk_mul_f32 v[28:29], v[28:29], v[108:109]
	v_pk_mul_f32 v[24:25], v[24:25], v[112:113]
	v_pk_mul_f32 v[20:21], v[20:21], v[116:117]
	v_pk_mul_f32 v[30:31], v[30:31], v[102:103]
	v_pk_mul_f32 v[26:27], v[26:27], v[106:107]
	v_pk_mul_f32 v[22:23], v[22:23], v[110:111]
	v_pk_mul_f32 v[18:19], v[18:19], v[114:115]
	v_pk_mul_f32 v[16:17], v[16:17], v[104:105]
	v_pk_mul_f32 v[12:13], v[12:13], v[108:109]
	v_pk_mul_f32 v[8:9], v[8:9], v[112:113]
	v_pk_mul_f32 v[4:5], v[4:5], v[116:117]
	v_pk_mul_f32 v[14:15], v[14:15], v[102:103]
	v_pk_mul_f32 v[10:11], v[10:11], v[106:107]
	v_pk_mul_f32 v[6:7], v[6:7], v[110:111]
	v_pk_mul_f32 v[2:3], v[2:3], v[114:115]
	s_branch .Lh1_noresc
; __device__ __forceinline__ void mask_tile(f32x16& p0, f32x16& p1, int dq, unsigned W) {
;     const float NEG = -__builtin_inff();
; #pragma unroll
;     for (int r = 0; r < 16; ++r) {
;         const int c = (r & 3) + 8 * (r >> 2);
;         if ((unsigned)(dq - c) >= W) p0[r] = NEG;
;         if ((unsigned)(dq - c - 32) >= W) p1[r] = NEG;
;     }
; }
.Lh2_mask:
	v_add_u32_e32 v226, s80, v222
	v_add_u32_e32 v66, 0xffffff80, v226
	v_cmp_gt_u32_e32 vcc, s85, v66
	v_add_u32_e32 v66, 0xffffff60, v226
	s_nop 0
	v_cndmask_b32_e32 v114, v215, v114, vcc
	v_cmp_gt_u32_e32 vcc, s85, v66
	v_add_u32_e32 v66, 0xffffff7f, v226
	s_nop 0
	v_cndmask_b32_e32 v98, v215, v98, vcc
	v_cmp_gt_u32_e32 vcc, s85, v66
	v_add_u32_e32 v66, 0xffffff5f, v226
	s_nop 0
	v_cndmask_b32_e32 v115, v215, v115, vcc
	v_cmp_gt_u32_e32 vcc, s85, v66
	v_add_u32_e32 v66, 0xffffff7e, v226
	s_nop 0
	v_cndmask_b32_e32 v99, v215, v99, vcc
	v_cmp_gt_u32_e32 vcc, s85, v66
	v_add_u32_e32 v66, 0xffffff5e, v226
	s_nop 0
	v_cndmask_b32_e32 v116, v215, v116, vcc
	v_cmp_gt_u32_e32 vcc, s85, v66
	v_add_u32_e32 v66, 0xffffff7d, v226
	s_nop 0
	v_cndmask_b32_e32 v100, v215, v100, vcc
	v_cmp_gt_u32_e32 vcc, s85, v66
	v_add_u32_e32 v66, 0xffffff5d, v226
	s_nop 0
	v_cndmask_b32_e32 v117, v215, v117, vcc
	v_cmp_gt_u32_e32 vcc, s85, v66
	v_add_u32_e32 v66, 0xffffff78, v226
	s_nop 0
	v_cndmask_b32_e32 v101, v215, v101, vcc
	v_cmp_gt_u32_e32 vcc, s85, v66
	v_add_u32_e32 v66, 0xffffff58, v226
	s_nop 0
	v_cndmask_b32_e32 v118, v215, v118, vcc
	v_cmp_gt_u32_e32 vcc, s85, v66
	v_add_u32_e32 v66, 0xffffff77, v226
	s_nop 0
	v_cndmask_b32_e32 v102, v215, v102, vcc
	v_cmp_gt_u32_e32 vcc, s85, v66
	v_add_u32_e32 v66, 0xffffff57, v226
	s_nop 0
	v_cndmask_b32_e32 v119, v215, v119, vcc
	v_cmp_gt_u32_e32 vcc, s85, v66
	v_add_u32_e32 v66, 0xffffff76, v226
	s_nop 0
	v_cndmask_b32_e32 v103, v215, v103, vcc
	v_cmp_gt_u32_e32 vcc, s85, v66
	v_add_u32_e32 v66, 0xffffff56, v226
	s_nop 0
	v_cndmask_b32_e32 v120, v215, v120, vcc
	v_cmp_gt_u32_e32 vcc, s85, v66
	v_add_u32_e32 v66, 0xffffff75, v226
	s_nop 0
	v_cndmask_b32_e32 v104, v215, v104, vcc
	v_cmp_gt_u32_e32 vcc, s85, v66
	v_add_u32_e32 v66, 0xffffff55, v226
	s_nop 0
	v_cndmask_b32_e32 v121, v215, v121, vcc
	v_cmp_gt_u32_e32 vcc, s85, v66
	v_add_u32_e32 v66, 0xffffff70, v226
	s_nop 0
	v_cndmask_b32_e32 v105, v215, v105, vcc
	v_cmp_gt_u32_e32 vcc, s85, v66
	v_add_u32_e32 v66, 0xffffff50, v226
	s_nop 0
	v_cndmask_b32_e32 v122, v215, v122, vcc
	v_cmp_gt_u32_e32 vcc, s85, v66
	v_add_u32_e32 v66, 0xffffff6f, v226
	s_nop 0
	v_cndmask_b32_e32 v106, v215, v106, vcc
	v_cmp_gt_u32_e32 vcc, s85, v66
	v_add_u32_e32 v66, 0xffffff4f, v226
	s_nop 0
	v_cndmask_b32_e32 v123, v215, v123, vcc
	v_cmp_gt_u32_e32 vcc, s85, v66
	v_add_u32_e32 v66, 0xffffff6e, v226
	s_nop 0
	v_cndmask_b32_e32 v107, v215, v107, vcc
	v_cmp_gt_u32_e32 vcc, s85, v66
	v_add_u32_e32 v66, 0xffffff4e, v226
	s_nop 0
	v_cndmask_b32_e32 v124, v215, v124, vcc
	v_cmp_gt_u32_e32 vcc, s85, v66
	v_add_u32_e32 v66, 0xffffff6d, v226
	s_nop 0
	v_cndmask_b32_e32 v108, v215, v108, vcc
	v_cmp_gt_u32_e32 vcc, s85, v66
	v_add_u32_e32 v66, 0xffffff4d, v226
	s_nop 0
	v_cndmask_b32_e32 v125, v215, v125, vcc
	v_cmp_gt_u32_e32 vcc, s85, v66
	v_add_u32_e32 v66, 0xffffff68, v226
	s_nop 0
	v_cndmask_b32_e32 v109, v215, v109, vcc
	v_cmp_gt_u32_e32 vcc, s85, v66
	v_add_u32_e32 v66, 0xffffff48, v226
	s_nop 0
	v_cndmask_b32_e32 v126, v215, v126, vcc
	v_cmp_gt_u32_e32 vcc, s85, v66
	v_add_u32_e32 v66, 0xffffff67, v226
	s_nop 0
	v_cndmask_b32_e32 v110, v215, v110, vcc
	v_cmp_gt_u32_e32 vcc, s85, v66
	v_add_u32_e32 v66, 0xffffff47, v226
	s_nop 0
	v_cndmask_b32_e32 v127, v215, v127, vcc
	v_cmp_gt_u32_e32 vcc, s85, v66
	v_add_u32_e32 v66, 0xffffff66, v226
	s_nop 0
	v_cndmask_b32_e32 v111, v215, v111, vcc
	v_cmp_gt_u32_e32 vcc, s85, v66
	v_add_u32_e32 v66, 0xffffff46, v226
	s_nop 0
	v_cndmask_b32_e32 v128, v215, v128, vcc
	v_cmp_gt_u32_e32 vcc, s85, v66
	v_add_u32_e32 v66, 0xffffff65, v226
	s_nop 0
	v_cndmask_b32_e32 v112, v215, v112, vcc
	v_cmp_gt_u32_e32 vcc, s85, v66
	v_add_u32_e32 v66, 0xffffff45, v226
	s_nop 0
	v_cndmask_b32_e32 v129, v215, v129, vcc
	v_cmp_gt_u32_e32 vcc, s85, v66
	s_nop 1
	v_cndmask_b32_e32 v113, v215, v113, vcc
	s_branch .Lh2_nomask
.Lh2_resc:
	s_and_saveexec_b64 s[52:53], s[0:1]
	ds_write_b32 v219, v254 offset:128
	s_or_b64 exec, exec, s[52:53]
	s_waitcnt lgkmcnt(0)
	ds_read_b128 v[164:167], v218 offset:224
	ds_read_b128 v[168:171], v218 offset:192
	ds_read_b128 v[172:175], v218 offset:160
	ds_read_b128 v[180:183], v218 offset:128
	s_waitcnt lgkmcnt(3)
	v_pk_mul_f32 v[48:49], v[48:49], v[166:167]
	s_waitcnt lgkmcnt(2)
	v_pk_mul_f32 v[44:45], v[44:45], v[170:171]
	s_waitcnt lgkmcnt(1)
	v_pk_mul_f32 v[40:41], v[40:41], v[174:175]
	s_waitcnt lgkmcnt(0)
	v_pk_mul_f32 v[36:37], v[36:37], v[182:183]
	v_pk_mul_f32 v[46:47], v[46:47], v[164:165]
	v_pk_mul_f32 v[42:43], v[42:43], v[168:169]
	v_pk_mul_f32 v[38:39], v[38:39], v[172:173]
	v_pk_mul_f32 v[34:35], v[34:35], v[180:181]
	v_pk_mul_f32 v[64:65], v[64:65], v[166:167]
	v_pk_mul_f32 v[60:61], v[60:61], v[170:171]
	v_pk_mul_f32 v[56:57], v[56:57], v[174:175]
	v_pk_mul_f32 v[52:53], v[52:53], v[182:183]
	v_pk_mul_f32 v[62:63], v[62:63], v[164:165]
	v_pk_mul_f32 v[58:59], v[58:59], v[168:169]
	v_pk_mul_f32 v[54:55], v[54:55], v[172:173]
	v_pk_mul_f32 v[50:51], v[50:51], v[180:181]
	v_pk_mul_f32 v[32:33], v[32:33], v[166:167]
	v_pk_mul_f32 v[28:29], v[28:29], v[170:171]
	v_pk_mul_f32 v[24:25], v[24:25], v[174:175]
	v_pk_mul_f32 v[20:21], v[20:21], v[182:183]
	v_pk_mul_f32 v[30:31], v[30:31], v[164:165]
	v_pk_mul_f32 v[26:27], v[26:27], v[168:169]
	v_pk_mul_f32 v[22:23], v[22:23], v[172:173]
	v_pk_mul_f32 v[18:19], v[18:19], v[180:181]
	v_pk_mul_f32 v[16:17], v[16:17], v[166:167]
	v_pk_mul_f32 v[12:13], v[12:13], v[170:171]
	v_pk_mul_f32 v[8:9], v[8:9], v[174:175]
	v_pk_mul_f32 v[4:5], v[4:5], v[182:183]
	v_pk_mul_f32 v[14:15], v[14:15], v[164:165]
	v_pk_mul_f32 v[10:11], v[10:11], v[168:169]
	v_pk_mul_f32 v[6:7], v[6:7], v[172:173]
	v_pk_mul_f32 v[2:3], v[2:3], v[180:181]
	s_branch .Lh2_noresc
.Lh2_pvt_nowrite:
	v_mfma_f32_32x32x16_bf16 v[2:17], v[178:181], v[86:89], v[2:17]
	v_fmamk_f32 v129, v109, 0x3e0293ee, v253
	v_fmamk_f32 v122, v110, 0x3e0293ee, v253
	v_fmamk_f32 v123, v111, 0x3e0293ee, v253
	v_mfma_f32_32x32x16_bf16 v[2:17], v[182:185], v[90:93], v[2:17]
	v_fmamk_f32 v118, v112, 0x3e0293ee, v253
	v_fmamk_f32 v119, v113, 0x3e0293ee, v253
	v_add_f32_e32 v98, v223, v224
	v_mfma_f32_32x32x16_bf16 v[2:17], v[186:189], v[94:97], v[2:17]
	v_fmac_f32_e32 v98, v197, v221
	v_add_f32_e32 v221, v228, v229
	v_fmac_f32_e32 v221, v98, v225
	v_mfma_f32_32x32x16_bf16 v[2:17], v[190:193], v[246:249], v[2:17]
	s_branch .Lh2_pvt_join
